# gemm_out and peer_q K loops: SADDR-form tile loads (scalar tile+k base, constant per-thread row offsets), as in gemm_z
# speedup vs baseline: 1.0080x; 1.0031x over previous
; DEVI int prow_of(int rr) { return (rr >> 12) * TP + NMETA + (rr & 4095); }
; DEVI const float* hrow_ptr(const P& p, int prow, bool& zero) {
;   const int b = prow / TP, tt = prow - b * TP;
;   zero = false;
;   if (tt < NMETA) return p.in[1] + (size_t)tt * DM;
;   if (tt < NMETA + SEQ) return p.in[0] + ((size_t)b * SEQ + (tt - NMETA)) * DM;
;   zero = true; return p.in[0];
;     ...
;     for (int i = 0; i < 4; i++) arow[i] = (const char*)(mixed + (size_t)prow_of(mt * 128 + (var == 3 ? 0 : r0 + 32 * i)) * 1024);
;     gemm_core<0, false, true, 1024>(smem, arow, az, (const uint16_t*)(p.ws + WS_WT_OUT), nt * 128, nt, var >= 2 ? 0 : 0xffff, var == 3 ? 0 : 1);
.LBB0_359:
	s_and_b32 s0, s38, 0x1fffff8
	s_or_b32 s24, s0, s33
	s_lshr_b32 s30, s38, 3
	s_and_b64 s[0:1], s[54:55], exec
	s_cselect_b32 s0, s24, s30
	s_lshl_b32 s24, s0, 7
	v_add_u32_e32 v2, s24, v129
	v_ashrrev_i32_e32 v0, 12, v2
	v_mul_i32_i24_e32 v0, 0x1080, v0
	v_and_b32_e32 v1, 0xfff, v2
	v_add3_u32 v0, v1, v0, 16
	v_ashrrev_i32_e32 v1, 31, v0
	v_lshlrev_b64 v[0:1], 11, v[0:1]
	v_lshl_add_u64 v[132:133], s[26:27], 0, v[0:1]
	v_add_u32_e32 v0, 32, v2
	v_ashrrev_i32_e32 v1, 12, v0
	v_mul_i32_i24_e32 v1, 0x1080, v1
	v_and_b32_e32 v0, 0xfff, v0
	v_add3_u32 v0, v0, v1, 16
	v_ashrrev_i32_e32 v1, 31, v0
	v_lshlrev_b64 v[0:1], 11, v[0:1]
	v_lshl_add_u64 v[134:135], s[26:27], 0, v[0:1]
	v_add_u32_e32 v0, 64, v2
	v_ashrrev_i32_e32 v1, 12, v0
	v_mul_i32_i24_e32 v1, 0x1080, v1
	v_and_b32_e32 v0, 0xfff, v0
	v_add3_u32 v0, v0, v1, 16
	v_ashrrev_i32_e32 v1, 31, v0
	v_lshlrev_b64 v[0:1], 11, v[0:1]
	v_lshl_add_u64 v[136:137], s[26:27], 0, v[0:1]
	v_add_u32_e32 v0, 0x60, v2
	v_ashrrev_i32_e32 v1, 12, v0
	v_mul_i32_i24_e32 v1, 0x1080, v1
	v_and_b32_e32 v0, 0xfff, v0
	v_add3_u32 v0, v0, v1, 16
	v_ashrrev_i32_e32 v1, 31, v0
	s_and_b32 s0, s38, 7
	v_mov_b32_e32 v38, v178
	v_lshlrev_b64 v[0:1], 11, v[0:1]
	s_lshl_b32 s39, s0, 7
	v_lshl_add_u64 v[138:139], s[26:27], 0, v[0:1]
	v_ashrrev_i32_e32 v40, 3, v38
	v_add_u32_e32 v0, s39, v40
	v_ashrrev_i32_e32 v1, 31, v0
	v_and_b32_e32 v39, 7, v38
	v_lshlrev_b64 v[0:1], 11, v[0:1]
	s_barrier
	s_ashr_i32 s1, s0, 31
	v_lshl_add_u64 v[0:1], s[22:23], 0, v[0:1]
	v_lshlrev_b32_e32 v130, 4, v39
	s_lshl_b64 s[30:31], s[0:1], 7
	v_lshl_add_u64 v[140:141], v[0:1], 0, v[130:131]
	v_or_b32_e32 v0, s30, v130
	v_mov_b32_e32 v1, s31
	v_lshl_or_b32 v250, v129, 11, v130
	v_add_u32_e32 v251, 0x10000, v250
	v_add_u32_e32 v252, 0x20000, v250
	v_add_u32_e32 v253, 0x30000, v250
	s_lshr_b32 s98, s24, 12
	s_mulk_i32 s98, 0x1080
	s_and_b32 s99, s24, 0xfff
	s_add_i32 s98, s98, s99
	s_add_i32 s98, s98, 16
	s_lshl_b32 s98, s98, 11
	s_add_u32 s98, s26, s98
	s_addc_u32 s99, s27, 0
	s_lshl_b32 s100, s39, 11
	s_add_u32 s100, s22, s100
	s_addc_u32 s101, s23, 0
	s_mov_b64 s[30:31], 0x10000
	s_lshl_b32 s0, s0, 6
	v_lshl_add_u64 v[142:143], v[140:141], 0, s[30:31]
	s_mov_b64 s[30:31], 0x20000
	s_ashr_i32 s1, s0, 31
	v_lshl_add_u64 v[144:145], v[140:141], 0, s[30:31]
	s_mov_b64 s[30:31], 0x30000
	s_lshl_b64 s[0:1], s[0:1], 1
	v_lshl_add_u64 v[146:147], v[140:141], 0, s[30:31]
	v_lshl_add_u64 v[4:5], v[132:133], 0, v[0:1]
	v_lshl_add_u64 v[2:3], v[140:141], 0, s[0:1]
	v_lshl_add_u64 v[12:13], v[134:135], 0, v[0:1]
	v_lshl_add_u64 v[8:9], v[142:143], 0, s[0:1]
	v_lshl_add_u64 v[20:21], v[136:137], 0, v[0:1]
	v_lshl_add_u64 v[16:17], v[144:145], 0, s[0:1]
	v_lshl_add_u64 v[24:25], v[138:139], 0, v[0:1]
	v_lshl_add_u64 v[28:29], v[146:147], 0, s[0:1]
	global_load_dwordx4 v[0:3], v[2:3], off
	s_nop 0
	global_load_dwordx4 v[4:7], v[4:5], off
	s_nop 0
	global_load_dwordx4 v[8:11], v[8:9], off
	s_nop 0
	global_load_dwordx4 v[12:15], v[12:13], off
	s_nop 0
	global_load_dwordx4 v[16:19], v[16:17], off
	s_nop 0
	global_load_dwordx4 v[20:23], v[20:21], off
	s_nop 0
	global_load_dwordx4 v[24:27], v[24:25], off
	s_nop 0
	global_load_dwordx4 v[28:31], v[28:29], off
	s_add_i32 s0, s38, 1
	s_and_b32 s0, s0, 7
	s_ashr_i32 s1, s0, 31
	v_mul_lo_u32 v32, v40, s35
	s_lshl_b64 s[30:31], s[0:1], 7
	s_lshl_b32 s0, s0, 6
	v_add3_u32 v151, 16, v32, v130
	v_or_b32_e32 v32, s30, v130
	v_mov_b32_e32 v33, s31
	s_ashr_i32 s1, s0, 31
	v_lshl_add_u64 v[34:35], v[132:133], 0, v[32:33]
	s_lshl_b64 s[0:1], s[0:1], 1
	v_lshl_add_u64 v[36:37], v[140:141], 0, s[0:1]
	global_load_dwordx4 v[64:67], v[34:35], off
	global_load_dwordx4 v[72:75], v[36:37], off
	v_lshl_add_u64 v[34:35], v[134:135], 0, v[32:33]
	v_lshl_add_u64 v[36:37], v[142:143], 0, s[0:1]
	global_load_dwordx4 v[68:71], v[34:35], off
	global_load_dwordx4 v[80:83], v[36:37], off
	v_lshl_add_u64 v[34:35], v[136:137], 0, v[32:33]
	v_lshl_add_u64 v[36:37], v[144:145], 0, s[0:1]
	global_load_dwordx4 v[76:79], v[34:35], off
	global_load_dwordx4 v[88:91], v[36:37], off
	v_lshl_add_u64 v[34:35], v[146:147], 0, s[0:1]
	s_add_i32 s0, s38, 2
	v_lshl_add_u64 v[32:33], v[138:139], 0, v[32:33]
	s_and_b32 s0, s0, 7
	global_load_dwordx4 v[84:87], v[32:33], off
	global_load_dwordx4 v[92:95], v[34:35], off
	v_mov_b32_e32 v168, v131
	v_mov_b32_e32 v159, v131
	v_mov_b32_e32 v169, v131
	v_mov_b32_e32 v170, v131
	v_bfe_u32 v152, v38, 6, 1
	v_and_b32_e32 v153, 31, v38
	v_bfe_u32 v154, v38, 5, 1
	v_cmp_eq_u32_e32 vcc, 0, v39
	v_lshl_add_u32 v160, v40, 2, s36
	v_add_u32_e32 v155, 0x1200, v151
	v_add_u32_e32 v156, 0x2400, v151
	v_add_u32_e32 v157, 0x3600, v151
	v_add_u32_e32 v161, 0x80, v160
	v_add_u32_e32 v163, 0x100, v160
	v_add_u32_e32 v164, 0x180, v160
	s_waitcnt vmcnt(14)
	ds_write_b128 v151, v[4:7]
	ds_write_b128 v151, v[0:3] offset:36864
	s_waitcnt vmcnt(12)
	ds_write_b128 v151, v[12:15] offset:4608
	ds_write_b128 v151, v[8:11] offset:41472
	s_waitcnt vmcnt(10)
	ds_write_b128 v151, v[20:23] offset:9216
	ds_write_b128 v151, v[16:19] offset:46080
	s_waitcnt vmcnt(9)
	ds_write_b128 v151, v[24:27] offset:13824
	s_waitcnt vmcnt(8)
	ds_write_b128 v151, v[28:31] offset:50688
	s_waitcnt lgkmcnt(0)
	s_barrier
; #define GL_LOAD(KT_, S) { int kt_ = MID ? (((KT_) & 8) | (((KT_) + rot) & 7)) : (((KT_) + rot) & (KT - 1)); kt_ &= ktmask; asm volatile("" : "+s"(kt_)); GL_LD1(0, S) GL_LD1(1, S) GL_LD1(2, S) GL_LD1(3, S) }
; #define GL_STORE(BUF_, S, DOSSQ_) { const bool dossq_ = (DOSSQ_); GL_ST1(0, S, BUF_, ssq0) GL_ST1(1, S, BUF_, ssq1) GL_ST1(2, S, BUF_, ssq2) GL_ST1(3, S, BUF_, ssq3) }
;     ...
;   if (KT <= 4) {
;     if (KT > 2) GL_LOAD(2, 0);
; #pragma unroll
;     for (int kt = 0; kt < KT; kt += 2) {
;       GL_COMPUTE(0);
;       GL_STORE(1, 1, true);
;       if (kt + 3 < KT) GL_LOAD(kt + 3, 1);
;       __syncthreads();
;       GL_COMPUTE(1);
;       if (kt + 2 < KT) {
;         GL_STORE(0, 0, true);
;         if (kt + 4 < KT) GL_LOAD(kt + 4, 0);
;       }
;       __syncthreads();
;     }
;   } else {
;     GL_LOAD(2, 0);
	s_ashr_i32 s1, s0, 31
	s_lshl_b64 s[30:31], s[0:1], 7
	s_lshl_b32 s0, s0, 6
	v_or_b32_e32 v0, s30, v130
	v_mov_b32_e32 v1, s31
	s_ashr_i32 s1, s0, 31
	v_lshl_add_u64 v[2:3], v[132:133], 0, v[0:1]
	s_lshl_b64 s[0:1], s[0:1], 1
	v_lshl_add_u64 v[8:9], v[140:141], 0, s[0:1]
	global_load_dwordx4 v[96:99], v[2:3], off
	global_load_dwordx4 v[112:115], v[8:9], off
	v_lshl_add_u64 v[2:3], v[134:135], 0, v[0:1]
	v_lshl_add_u64 v[8:9], v[142:143], 0, s[0:1]
	global_load_dwordx4 v[108:111], v[2:3], off
	global_load_dwordx4 v[116:119], v[8:9], off
	v_lshl_add_u64 v[2:3], v[136:137], 0, v[0:1]
	v_lshl_add_u64 v[0:1], v[138:139], 0, v[0:1]
	v_lshl_add_u64 v[8:9], v[144:145], 0, s[0:1]
	global_load_dwordx4 v[104:107], v[2:3], off
	global_load_dwordx4 v[120:123], v[8:9], off
	v_lshl_add_u64 v[2:3], v[146:147], 0, s[0:1]
	global_load_dwordx4 v[100:103], v[0:1], off
	global_load_dwordx4 v[124:127], v[2:3], off
	v_ashrrev_i32_e32 v0, 7, v38
	v_dot2c_f32_bf16_e32 v168, v12, v12
	v_dot2c_f32_bf16_e32 v159, v4, v4
	v_dot2c_f32_bf16_e32 v168, v13, v13
	v_dot2c_f32_bf16_e32 v169, v20, v20
	v_dot2c_f32_bf16_e32 v170, v24, v24
	v_lshlrev_b32_e32 v158, 6, v0
	v_dot2c_f32_bf16_e32 v159, v5, v5
	v_dot2c_f32_bf16_e32 v168, v14, v14
	v_dot2c_f32_bf16_e32 v169, v21, v21
	v_dot2c_f32_bf16_e32 v170, v25, v25
	v_or_b32_e32 v1, v158, v153
	v_lshlrev_b32_e32 v16, 4, v154
	v_lshl_or_b32 v2, v152, 6, v153
	v_dot2c_f32_bf16_e32 v159, v6, v6
	v_dot2c_f32_bf16_e32 v168, v15, v15
	v_dot2c_f32_bf16_e32 v169, v22, v22
	v_dot2c_f32_bf16_e32 v170, v26, v26
	v_add_u32_e32 v17, 16, v16
	v_lshl_add_u32 v18, v0, 8, s36
	v_mul_lo_u32 v19, v1, s35
	v_mul_u32_u24_e32 v20, 0x90, v2
	v_mov_b32_e32 v14, v131
	v_mov_b32_e32 v15, v131
	v_dot2c_f32_bf16_e32 v159, v7, v7
	v_dot2c_f32_bf16_e32 v169, v23, v23
	v_dot2c_f32_bf16_e32 v170, v27, v27
	v_mov_b32_e32 v0, v131
	v_mov_b32_e32 v1, v131
	v_mov_b32_e32 v2, v131
	v_mov_b32_e32 v3, v131
	v_mov_b32_e32 v4, v131
	v_mov_b32_e32 v5, v131
	v_mov_b32_e32 v6, v131
	v_mov_b32_e32 v7, v131
	v_mov_b32_e32 v8, v131
	v_mov_b32_e32 v9, v131
	v_mov_b32_e32 v10, v131
	v_mov_b32_e32 v11, v131
	v_mov_b32_e32 v12, v131
	v_mov_b32_e32 v13, v131
	v_add_u32_e32 v165, v18, v16
	v_add_u32_e32 v166, v17, v19
	v_add_u32_e32 v167, v17, v20
	v_mov_b64_e32 v[30:31], v[14:15]
	v_mov_b64_e32 v[46:47], v[14:15]
	v_mov_b64_e32 v[62:63], v[14:15]
	s_mov_b32 s40, -2
	v_mov_b64_e32 v[28:29], v[12:13]
	v_mov_b64_e32 v[26:27], v[10:11]
	v_mov_b64_e32 v[24:25], v[8:9]
	v_mov_b64_e32 v[22:23], v[6:7]
	v_mov_b64_e32 v[20:21], v[4:5]
	v_mov_b64_e32 v[18:19], v[2:3]
	v_mov_b64_e32 v[16:17], v[0:1]
	v_mov_b64_e32 v[44:45], v[12:13]
	v_mov_b64_e32 v[42:43], v[10:11]
	v_mov_b64_e32 v[40:41], v[8:9]
	v_mov_b64_e32 v[38:39], v[6:7]
	v_mov_b64_e32 v[36:37], v[4:5]
	v_mov_b64_e32 v[34:35], v[2:3]
	v_mov_b64_e32 v[32:33], v[0:1]
	v_mov_b64_e32 v[60:61], v[12:13]
	v_mov_b64_e32 v[58:59], v[10:11]
	v_mov_b64_e32 v[56:57], v[8:9]
	v_mov_b64_e32 v[54:55], v[6:7]
	v_mov_b64_e32 v[52:53], v[4:5]
	v_mov_b64_e32 v[50:51], v[2:3]
	v_mov_b64_e32 v[48:49], v[0:1]
	s_branch .LBB0_362

; #define GL_LOAD(KT_, S) { int kt_ = MID ? (((KT_) & 8) | (((KT_) + rot) & 7)) : (((KT_) + rot) & (KT - 1)); kt_ &= ktmask; asm volatile("" : "+s"(kt_)); GL_LD1(0, S) GL_LD1(1, S) GL_LD1(2, S) GL_LD1(3, S) }
; #define GL_STORE(BUF_, S, DOSSQ_) { const bool dossq_ = (DOSSQ_); GL_ST1(0, S, BUF_, ssq0) GL_ST1(1, S, BUF_, ssq1) GL_ST1(2, S, BUF_, ssq2) GL_ST1(3, S, BUF_, ssq3) }
; #define GL_RS(DEN_) { GL_RS1(0, ssq0, DEN_) GL_RS1(1, ssq1, DEN_) GL_RS1(2, ssq2, DEN_) GL_RS1(3, ssq3, DEN_) }
;     ...
;     GL_LOAD(2, 0);
; #pragma unroll 1
;     for (int kt = 0; kt < KT; kt += 2) {
;       if (MID && kt == 8) {
;         GL_RS(512.f);
;         __syncthreads();
; #pragma unroll
;         for (int mi = 0; mi < 2; mi++) {
;           f32x16 sv;
; #pragma unroll
;           for (int r = 0; r < 16; r++) sv[r] = rs[64 * wm + 32 * mi + (r & 3) + 8 * (r >> 2) + 4 * lh];
;           acc[mi][0] *= sv; acc[mi][1] *= sv;
;         }
;       }
;       GL_COMPUTE(0);
;       GL_STORE(1, 1, !MID || (kt + 1) < 8);
;       GL_LOAD((kt + 3 < KT ? kt + 3 : KT - 1), 1);
;       __syncthreads();
;       GL_COMPUTE(1);
;       GL_STORE(0, 0, (kt + 2 < KT) && (!MID || (kt + 2) < 8));
;       GL_LOAD((kt + 4 < KT ? kt + 4 : KT - 1), 0);
;       __syncthreads();
;     }
.LBB0_361:
	ds_read_b128 v[172:175], v166
	ds_read_b128 v[180:183], v167 offset:36864
	ds_read_b128 v[184:187], v167 offset:41472
	s_add_i32 s40, s40, 2
	s_waitcnt lgkmcnt(1)
	v_mfma_f32_32x32x16_bf16 v[48:63], v[172:175], v[180:183], v[48:63]
	s_waitcnt lgkmcnt(0)
	v_mfma_f32_32x32x16_bf16 v[32:47], v[172:175], v[184:187], v[32:47]
	ds_read_b128 v[172:175], v166 offset:4608
	s_waitcnt lgkmcnt(0)
	v_mfma_f32_32x32x16_bf16 v[16:31], v[172:175], v[180:183], v[16:31]
	v_mfma_f32_32x32x16_bf16 v[0:15], v[172:175], v[184:187], v[0:15]
	ds_read_b128 v[172:175], v166 offset:32
	ds_read_b128 v[180:183], v167 offset:36896
	ds_read_b128 v[184:187], v167 offset:41504
	s_waitcnt lgkmcnt(1)
	v_mfma_f32_32x32x16_bf16 v[48:63], v[172:175], v[180:183], v[48:63]
	s_waitcnt lgkmcnt(0)
	v_mfma_f32_32x32x16_bf16 v[32:47], v[172:175], v[184:187], v[32:47]
	ds_read_b128 v[172:175], v166 offset:4640
	s_waitcnt lgkmcnt(0)
	v_mfma_f32_32x32x16_bf16 v[16:31], v[172:175], v[180:183], v[16:31]
	v_mfma_f32_32x32x16_bf16 v[0:15], v[172:175], v[184:187], v[0:15]
	ds_read_b128 v[172:175], v166 offset:64
	ds_read_b128 v[180:183], v167 offset:36928
	ds_read_b128 v[184:187], v167 offset:41536
	s_min_u32 s0, s40, 12
	s_add_i32 s0, s0, 3
	s_and_b32 s1, s0, 8
	s_waitcnt lgkmcnt(1)
	v_mfma_f32_32x32x16_bf16 v[48:63], v[172:175], v[180:183], v[48:63]
	s_add_i32 s0, s0, s38
	s_and_b32 s0, s0, 7
	s_or_b32 s0, s0, s1
	v_mov_b32_e32 v171, v159
	v_mov_b32_e32 v179, v170
	s_waitcnt vmcnt(15)
	v_dot2c_f32_bf16_e32 v171, v64, v64
	v_mov_b32_e32 v176, v168
	s_waitcnt lgkmcnt(0)
	v_mfma_f32_32x32x16_bf16 v[32:47], v[172:175], v[184:187], v[32:47]
	ds_read_b128 v[172:175], v166 offset:4672
	s_waitcnt vmcnt(8)
	v_dot2c_f32_bf16_e32 v179, v84, v84
	v_dot2c_f32_bf16_e32 v171, v65, v65
	v_dot2c_f32_bf16_e32 v176, v68, v68
	v_mov_b32_e32 v177, v169
	v_dot2c_f32_bf16_e32 v179, v85, v85
	v_dot2c_f32_bf16_e32 v171, v66, v66
	s_waitcnt lgkmcnt(0)
	v_mfma_f32_32x32x16_bf16 v[16:31], v[172:175], v[180:183], v[16:31]
	v_dot2c_f32_bf16_e32 v176, v69, v69
	v_dot2c_f32_bf16_e32 v177, v76, v76
	v_dot2c_f32_bf16_e32 v171, v67, v67
	v_dot2c_f32_bf16_e32 v176, v70, v70
	v_dot2c_f32_bf16_e32 v177, v77, v77
	v_dot2c_f32_bf16_e32 v179, v86, v86
	v_dot2c_f32_bf16_e32 v176, v71, v71
	v_mfma_f32_32x32x16_bf16 v[0:15], v[172:175], v[184:187], v[0:15]
	ds_read_b128 v[172:175], v166 offset:96
	ds_read_b128 v[180:183], v167 offset:36960
	ds_read_b128 v[184:187], v167 offset:41568
	v_dot2c_f32_bf16_e32 v177, v78, v78
	v_dot2c_f32_bf16_e32 v179, v87, v87
	v_dot2c_f32_bf16_e32 v177, v79, v79
	s_waitcnt lgkmcnt(1)
	v_mfma_f32_32x32x16_bf16 v[48:63], v[172:175], v[180:183], v[48:63]
	s_waitcnt lgkmcnt(0)
	v_mfma_f32_32x32x16_bf16 v[32:47], v[172:175], v[184:187], v[32:47]
	ds_read_b128 v[172:175], v166 offset:4704
	ds_write_b128 v151, v[64:67] offset:18432
	ds_write_b128 v151, v[72:75] offset:55296
	ds_write_b128 v155, v[68:71] offset:18432
	ds_write_b128 v155, v[80:83] offset:55296
	ds_write_b128 v156, v[76:79] offset:18432
	ds_write_b128 v156, v[88:91] offset:55296
	ds_write_b128 v157, v[84:87] offset:18432
	s_waitcnt vmcnt(8)
	ds_write_b128 v157, v[92:95] offset:55296
	s_lshl_b32 s0, s0, 7
	s_add_u32 s30, s98, s0
	s_addc_u32 s31, s99, 0
	s_add_u32 s0, s100, s0
	s_addc_u32 s1, s101, 0
	global_load_dwordx4 v[64:67], v250, s[30:31]
	global_load_dwordx4 v[72:75], v250, s[0:1]
	global_load_dwordx4 v[68:71], v251, s[30:31]
	global_load_dwordx4 v[80:83], v251, s[0:1]
	global_load_dwordx4 v[76:79], v252, s[30:31]
	s_waitcnt lgkmcnt(8)
	v_mfma_f32_32x32x16_bf16 v[16:31], v[172:175], v[180:183], v[16:31]
	global_load_dwordx4 v[88:91], v252, s[0:1]
	s_nop 0
	global_load_dwordx4 v[92:95], v253, s[0:1]
	s_nop 0
	global_load_dwordx4 v[84:87], v253, s[30:31]
	s_waitcnt lgkmcnt(0)
	s_barrier
; #define GL_LOAD(KT_, S) { int kt_ = MID ? (((KT_) & 8) | (((KT_) + rot) & 7)) : (((KT_) + rot) & (KT - 1)); kt_ &= ktmask; asm volatile("" : "+s"(kt_)); GL_LD1(0, S) GL_LD1(1, S) GL_LD1(2, S) GL_LD1(3, S) }
; #define GL_STORE(BUF_, S, DOSSQ_) { const bool dossq_ = (DOSSQ_); GL_ST1(0, S, BUF_, ssq0) GL_ST1(1, S, BUF_, ssq1) GL_ST1(2, S, BUF_, ssq2) GL_ST1(3, S, BUF_, ssq3) }
; #define GL_RS(DEN_) { GL_RS1(0, ssq0, DEN_) GL_RS1(1, ssq1, DEN_) GL_RS1(2, ssq2, DEN_) GL_RS1(3, ssq3, DEN_) }
;     ...
;     GL_LOAD(2, 0);
; #pragma unroll 1
;     for (int kt = 0; kt < KT; kt += 2) {
;       if (MID && kt == 8) {
;         GL_RS(512.f);
;         __syncthreads();
; #pragma unroll
;         for (int mi = 0; mi < 2; mi++) {
;           f32x16 sv;
; #pragma unroll
;           for (int r = 0; r < 16; r++) sv[r] = rs[64 * wm + 32 * mi + (r & 3) + 8 * (r >> 2) + 4 * lh];
;           acc[mi][0] *= sv; acc[mi][1] *= sv;
;         }
;       }
;       GL_COMPUTE(0);
;       GL_STORE(1, 1, !MID || (kt + 1) < 8);
;       GL_LOAD((kt + 3 < KT ? kt + 3 : KT - 1), 1);
;       __syncthreads();
;       GL_COMPUTE(1);
;       GL_STORE(0, 0, (kt + 2 < KT) && (!MID || (kt + 2) < 8));
;       GL_LOAD((kt + 4 < KT ? kt + 4 : KT - 1), 0);
;       __syncthreads();
;     }
	v_mfma_f32_32x32x16_bf16 v[0:15], v[172:175], v[184:187], v[0:15]
	ds_read_b128 v[172:175], v166 offset:18432
	ds_read_b128 v[180:183], v167 offset:55296
	ds_read_b128 v[184:187], v167 offset:59904
	s_waitcnt lgkmcnt(1)
	v_mfma_f32_32x32x16_bf16 v[48:63], v[172:175], v[180:183], v[48:63]
	s_waitcnt lgkmcnt(0)
	v_mfma_f32_32x32x16_bf16 v[32:47], v[172:175], v[184:187], v[32:47]
	ds_read_b128 v[172:175], v166 offset:23040
	s_waitcnt lgkmcnt(0)
	v_mfma_f32_32x32x16_bf16 v[16:31], v[172:175], v[180:183], v[16:31]
	v_mfma_f32_32x32x16_bf16 v[0:15], v[172:175], v[184:187], v[0:15]
	ds_read_b128 v[172:175], v166 offset:18464
	ds_read_b128 v[180:183], v167 offset:55328
	ds_read_b128 v[184:187], v167 offset:59936
	s_waitcnt lgkmcnt(1)
	v_mfma_f32_32x32x16_bf16 v[48:63], v[172:175], v[180:183], v[48:63]
	s_waitcnt lgkmcnt(0)
	v_mfma_f32_32x32x16_bf16 v[32:47], v[172:175], v[184:187], v[32:47]
	ds_read_b128 v[172:175], v166 offset:23072
	s_waitcnt lgkmcnt(0)
	v_mfma_f32_32x32x16_bf16 v[16:31], v[172:175], v[180:183], v[16:31]
	v_mfma_f32_32x32x16_bf16 v[0:15], v[172:175], v[184:187], v[0:15]
	ds_read_b128 v[172:175], v166 offset:23104
	ds_read_b128 v[180:183], v167 offset:59968
	ds_read_b128 v[184:187], v167 offset:55360
	ds_read_b128 v[188:191], v167 offset:55392
	ds_read_b128 v[192:195], v166 offset:18496
	ds_read_b128 v[196:199], v166 offset:18528
	s_cmp_lt_u32 s40, 8
	s_cselect_b64 s[0:1], -1, 0
	v_cndmask_b32_e64 v159, v159, v171, s[0:1]
	v_cndmask_b32_e64 v168, v168, v176, s[0:1]
	v_mov_b32_e32 v171, v159
	s_waitcnt lgkmcnt(1)
	v_mfma_f32_32x32x16_bf16 v[32:47], v[192:195], v[180:183], v[32:47]
	s_waitcnt vmcnt(10)
	v_dot2c_f32_bf16_e32 v171, v96, v96
	s_cmp_lt_u32 s40, 6
	v_cndmask_b32_e64 v169, v169, v177, s[0:1]
	v_cndmask_b32_e64 v170, v170, v179, s[0:1]
	s_cselect_b64 s[0:1], -1, 0
	v_dot2c_f32_bf16_e32 v171, v97, v97
	v_dot2c_f32_bf16_e32 v171, v98, v98
	v_mfma_f32_32x32x16_bf16 v[16:31], v[172:175], v[184:187], v[16:31]
	v_dot2c_f32_bf16_e32 v171, v99, v99
	s_nop 2
	v_cndmask_b32_e64 v159, v159, v171, s[0:1]
	v_mfma_f32_32x32x16_bf16 v[0:15], v[172:175], v[180:183], v[0:15]
	ds_read_b128 v[172:175], v167 offset:60000
	ds_read_b128 v[180:183], v166 offset:23136
	ds_write_b128 v151, v[96:99]
	s_waitcnt vmcnt(14)
	ds_write_b128 v151, v[112:115] offset:36864
	v_mov_b32_e32 v96, v168
	s_waitcnt vmcnt(13)
	v_dot2c_f32_bf16_e32 v96, v108, v108
	v_dot2c_f32_bf16_e32 v96, v109, v109
	v_dot2c_f32_bf16_e32 v96, v110, v110
	v_dot2c_f32_bf16_e32 v96, v111, v111
	ds_write_b128 v155, v[108:111]
	s_waitcnt vmcnt(12)
	ds_write_b128 v155, v[116:119] offset:36864
	s_waitcnt vmcnt(11)
	ds_write_b128 v156, v[104:107]
	s_waitcnt vmcnt(9)
	ds_write_b128 v156, v[120:123] offset:36864
	v_cndmask_b32_e64 v168, v168, v96, s[0:1]
	v_mov_b32_e32 v96, v169
	v_dot2c_f32_bf16_e32 v96, v104, v104
	v_dot2c_f32_bf16_e32 v96, v105, v105
	v_dot2c_f32_bf16_e32 v96, v106, v106
	v_dot2c_f32_bf16_e32 v96, v107, v107
	s_waitcnt vmcnt(8)
	ds_write_b128 v157, v[100:103]
	s_waitcnt vmcnt(8)
	ds_write_b128 v157, v[124:127] offset:36864
	v_mfma_f32_32x32x16_bf16 v[48:63], v[192:195], v[184:187], v[48:63]
	v_cndmask_b32_e64 v169, v169, v96, s[0:1]
	v_mov_b32_e32 v96, v170
	v_dot2c_f32_bf16_e32 v96, v100, v100
	v_dot2c_f32_bf16_e32 v96, v101, v101
	v_dot2c_f32_bf16_e32 v96, v102, v102
	v_dot2c_f32_bf16_e32 v96, v103, v103
	s_waitcnt lgkmcnt(10)
	v_mfma_f32_32x32x16_bf16 v[48:63], v[196:199], v[188:191], v[48:63]
	s_nop 0
	v_cndmask_b32_e64 v170, v170, v96, s[0:1]
	s_min_u32 s0, s40, 11
	s_add_i32 s0, s0, 4
	s_and_b32 s1, s0, 8
	s_add_i32 s0, s0, s38
	s_and_b32 s0, s0, 7
	s_or_b32 s0, s0, s1
	s_lshl_b32 s0, s0, 7
	s_add_u32 s30, s98, s0
	s_addc_u32 s31, s99, 0
	s_add_u32 s0, s100, s0
	s_addc_u32 s1, s101, 0
	global_load_dwordx4 v[112:115], v250, s[0:1]
	global_load_dwordx4 v[124:127], v253, s[0:1]
	global_load_dwordx4 v[108:111], v251, s[30:31]
	global_load_dwordx4 v[116:119], v251, s[0:1]
	global_load_dwordx4 v[104:107], v252, s[30:31]
	global_load_dwordx4 v[96:99], v250, s[30:31]
	s_waitcnt lgkmcnt(9)
	v_mfma_f32_32x32x16_bf16 v[32:47], v[196:199], v[172:175], v[32:47]
	global_load_dwordx4 v[120:123], v252, s[0:1]
	s_cmp_lt_u32 s40, 14
	global_load_dwordx4 v[100:103], v253, s[30:31]
	s_waitcnt lgkmcnt(0)
	s_barrier
	v_mfma_f32_32x32x16_bf16 v[16:31], v[180:183], v[188:191], v[16:31]
	v_mfma_f32_32x32x16_bf16 v[0:15], v[180:183], v[172:175], v[0:15]
	s_cbranch_scc0 .LBB0_358

; #define GL_LOAD(KT_, S) { int kt_ = MID ? (((KT_) & 8) | (((KT_) + rot) & 7)) : (((KT_) + rot) & (KT - 1)); kt_ &= ktmask; asm volatile("" : "+s"(kt_)); GL_LD1(0, S) GL_LD1(1, S) GL_LD1(2, S) GL_LD1(3, S) }
; #define GL_STORE(BUF_, S, DOSSQ_) { const bool dossq_ = (DOSSQ_); GL_ST1(0, S, BUF_, ssq0) GL_ST1(1, S, BUF_, ssq1) GL_ST1(2, S, BUF_, ssq2) GL_ST1(3, S, BUF_, ssq3) }
;     ...
;   __syncthreads();
;   GL_LOAD(0, 0);
;   GL_LOAD(1, 1);
;   GL_STORE(0, 0, true);
;   __syncthreads();
;   if (KT <= 4) {
;     if (KT > 2) GL_LOAD(2, 0);
; #pragma unroll
;     for (int kt = 0; kt < KT; kt += 2) {
; __device__ void phase_peer_q(const P& p, int vb, int nvb, char* smem) {
;     ...
;     for (int i = 0; i < 4; i++) arow[i] = p.ws + WS_HB + (size_t)(mt * 128 + r0 + 32 * i) * 2048;
;     gemm_core<0, false, false, 1024>(smem, arow, az, (const uint16_t*)(p.ws + WS_WT_PQ), hd * 128, hd * 2);
.LBB0_426:
	s_and_b32 s0, s56, 0x1fffff8
	s_or_b32 s36, s0, s33
	s_lshr_b32 s38, s56, 3
	s_and_b64 s[0:1], s[54:55], exec
	s_cselect_b32 s0, s36, s38
	s_lshl_b32 s46, s0, 7
	v_add_u32_e32 v0, s46, v163
	v_ashrrev_i32_e32 v1, 31, v0
	v_mov_b32_e32 v32, v178
	v_lshlrev_b64 v[0:1], 11, v[0:1]
	s_and_b32 s36, s56, 7
	v_lshl_add_u64 v[146:147], s[52:53], 0, v[0:1]
	v_ashrrev_i32_e32 v169, 3, v32
	s_lshl_b32 s47, s36, 1
	v_lshl_add_u32 v0, s36, 7, v169
	v_ashrrev_i32_e32 v1, 31, v0
	s_mov_b32 s0, s47
	v_and_b32_e32 v168, 7, v32
	v_lshlrev_b64 v[0:1], 11, v[0:1]
	s_barrier
	s_ashr_i32 s1, s0, 31
	v_lshl_add_u64 v[0:1], s[68:69], 0, v[0:1]
	v_lshlrev_b32_e32 v144, 4, v168
	s_lshl_b64 s[38:39], s[0:1], 7
	s_lshl_b32 s0, s0, 6
	v_lshl_add_u64 v[150:151], v[146:147], 0, s[30:31]
	v_lshl_add_u64 v[152:153], v[146:147], 0, s[34:35]
	v_lshl_add_u64 v[154:155], v[0:1], 0, v[144:145]
	v_or_b32_e32 v12, s38, v144
	v_mov_b32_e32 v13, s39
	s_ashr_i32 s1, s0, 31
	v_lshl_add_u64 v[148:149], v[146:147], 0, s[28:29]
	v_lshl_add_u64 v[16:17], v[146:147], 0, v[12:13]
	s_lshl_b64 s[0:1], s[0:1], 1
	v_lshl_add_u64 v[24:25], v[150:151], 0, v[12:13]
	v_lshl_add_u64 v[158:159], v[154:155], 0, s[30:31]
	v_lshl_add_u64 v[28:29], v[152:153], 0, v[12:13]
	v_lshl_add_u64 v[160:161], v[154:155], 0, s[34:35]
	v_mul_lo_u32 v18, v169, s40
	v_lshl_add_u64 v[0:1], v[154:155], 0, s[0:1]
	v_lshl_add_u64 v[20:21], v[148:149], 0, v[12:13]
	v_lshl_add_u64 v[8:9], v[158:159], 0, s[0:1]
	v_lshl_add_u64 v[12:13], v[160:161], 0, s[0:1]
	v_add3_u32 v170, 16, v18, v144
	global_load_dwordx4 v[16:19], v[16:17], off
	v_lshl_add_u64 v[156:157], v[154:155], 0, s[28:29]
	global_load_dwordx4 v[24:27], v[24:25], off
	v_lshl_add_u64 v[4:5], v[156:157], 0, s[0:1]
	global_load_dwordx4 v[28:31], v[28:29], off
	s_or_b32 s0, s47, 1
	global_load_dwordx4 v[0:3], v[0:1], off
	v_mov_b32_e32 v172, v145
	global_load_dwordx4 v[8:11], v[8:9], off
	v_mov_b32_e32 v175, v145
	global_load_dwordx4 v[12:15], v[12:13], off
	v_mov_b32_e32 v176, v145
	global_load_dwordx4 v[20:23], v[20:21], off
	v_mov_b32_e32 v177, v145
	global_load_dwordx4 v[4:7], v[4:5], off
	s_ashr_i32 s1, s0, 31
	s_lshl_b64 s[38:39], s[0:1], 7
	s_lshl_b32 s0, s0, 6
	v_or_b32_e32 v34, s38, v144
	v_mov_b32_e32 v35, s39
	s_ashr_i32 s1, s0, 31
	v_lshl_add_u64 v[36:37], v[146:147], 0, v[34:35]
	s_lshl_b64 s[0:1], s[0:1], 1
	global_load_dwordx4 v[84:87], v[36:37], off
	v_lshl_add_u64 v[36:37], v[154:155], 0, s[0:1]
	global_load_dwordx4 v[64:67], v[36:37], off
	v_lshl_add_u64 v[36:37], v[148:149], 0, v[34:35]
	global_load_dwordx4 v[116:119], v[36:37], off
	v_lshl_add_u64 v[36:37], v[156:157], 0, s[0:1]
	global_load_dwordx4 v[68:71], v[36:37], off
	v_lshl_add_u64 v[36:37], v[150:151], 0, v[34:35]
	v_lshl_add_u64 v[34:35], v[152:153], 0, v[34:35]
	global_load_dwordx4 v[120:123], v[36:37], off
	global_load_dwordx4 v[124:127], v[34:35], off
	v_lshl_add_u64 v[36:37], v[158:159], 0, s[0:1]
	v_lshl_add_u64 v[34:35], v[160:161], 0, s[0:1]
	s_add_i32 s0, s47, 2
	s_and_b32 s0, s0, 14
	global_load_dwordx4 v[72:75], v[36:37], off
	global_load_dwordx4 v[76:79], v[34:35], off
	v_bfe_u32 v165, v32, 6, 1
	v_and_b32_e32 v166, 31, v32
	v_bfe_u32 v167, v32, 5, 1
	v_add_u32_e32 v171, 0x1200, v170
	s_waitcnt vmcnt(15)
	ds_write_b128 v170, v[16:19]
	s_waitcnt vmcnt(12)
	ds_write_b128 v170, v[0:3] offset:36864
	s_waitcnt vmcnt(9)
	ds_write_b128 v170, v[20:23] offset:4608
	s_waitcnt vmcnt(8)
	ds_write_b128 v170, v[4:7] offset:41472
	ds_write_b128 v170, v[24:27] offset:9216
	ds_write_b128 v170, v[8:11] offset:46080
	ds_write_b128 v170, v[28:31] offset:13824
	ds_write_b128 v170, v[12:15] offset:50688
	s_waitcnt lgkmcnt(0)
	s_barrier
	s_ashr_i32 s1, s0, 31
	s_lshl_b64 s[38:39], s[0:1], 7
	s_lshl_b32 s0, s0, 6
	v_or_b32_e32 v0, s38, v144
	v_mov_b32_e32 v1, s39
	s_ashr_i32 s1, s0, 31
	v_lshl_add_u64 v[2:3], v[146:147], 0, v[0:1]
	s_lshl_b64 s[0:1], s[0:1], 1
	global_load_dwordx4 v[80:83], v[2:3], off
	v_lshl_add_u64 v[2:3], v[154:155], 0, s[0:1]
	global_load_dwordx4 v[108:111], v[2:3], off
	v_lshl_add_u64 v[2:3], v[148:149], 0, v[0:1]
	global_load_dwordx4 v[96:99], v[2:3], off
	v_lshl_add_u64 v[2:3], v[156:157], 0, s[0:1]
	global_load_dwordx4 v[104:107], v[2:3], off
	v_lshl_add_u64 v[2:3], v[150:151], 0, v[0:1]
	v_lshl_add_u64 v[0:1], v[152:153], 0, v[0:1]
	global_load_dwordx4 v[92:95], v[2:3], off
	global_load_dwordx4 v[88:91], v[0:1], off
	v_lshl_add_u64 v[2:3], v[158:159], 0, s[0:1]
	v_lshl_add_u64 v[0:1], v[160:161], 0, s[0:1]
	global_load_dwordx4 v[100:103], v[2:3], off
	global_load_dwordx4 v[112:115], v[0:1], off
	v_ashrrev_i32_e32 v0, 1, v32
	v_dot2c_f32_bf16_e32 v172, v16, v16
	v_dot2c_f32_bf16_e32 v175, v20, v20
	v_dot2c_f32_bf16_e32 v176, v24, v24
	v_dot2c_f32_bf16_e32 v177, v28, v28
	v_and_b32_e32 v179, 0xffffffc0, v0
	v_dot2c_f32_bf16_e32 v172, v17, v17
	v_dot2c_f32_bf16_e32 v175, v21, v21
	v_dot2c_f32_bf16_e32 v176, v25, v25
	v_dot2c_f32_bf16_e32 v177, v29, v29
	v_or_b32_e32 v0, v179, v166
	v_lshl_or_b32 v2, v165, 6, v166
	v_dot2c_f32_bf16_e32 v172, v18, v18
	v_dot2c_f32_bf16_e32 v175, v22, v22
	v_dot2c_f32_bf16_e32 v176, v26, v26
	v_dot2c_f32_bf16_e32 v177, v30, v30
	v_lshl_add_u32 v1, v167, 4, 16
	v_mul_lo_u32 v0, v0, s40
	v_mul_u32_u24_e32 v2, 0x90, v2
	v_dot2c_f32_bf16_e32 v172, v19, v19
	v_dot2c_f32_bf16_e32 v175, v23, v23
	v_add_u32_e32 v173, 0x2400, v170
	v_dot2c_f32_bf16_e32 v176, v27, v27
	v_add_u32_e32 v174, 0x3600, v170
	v_dot2c_f32_bf16_e32 v177, v31, v31
	s_add_i32 s0, s47, 3
	s_add_i32 s1, s47, 4
	v_add_u32_e32 v180, v1, v0
	v_add_u32_e32 v181, v1, v2
	s_mov_b32 s38, 0
	v_mov_b32_e32 v0, v145
	v_mov_b32_e32 v1, v145
	v_mov_b32_e32 v2, v145
	v_mov_b32_e32 v3, v145
; #define GL_LOAD(KT_, S) { int kt_ = MID ? (((KT_) & 8) | (((KT_) + rot) & 7)) : (((KT_) + rot) & (KT - 1)); kt_ &= ktmask; asm volatile("" : "+s"(kt_)); GL_LD1(0, S) GL_LD1(1, S) GL_LD1(2, S) GL_LD1(3, S) }
; #define GL_STORE(BUF_, S, DOSSQ_) { const bool dossq_ = (DOSSQ_); GL_ST1(0, S, BUF_, ssq0) GL_ST1(1, S, BUF_, ssq1) GL_ST1(2, S, BUF_, ssq2) GL_ST1(3, S, BUF_, ssq3) }
; #define GL_RS(DEN_) { GL_RS1(0, ssq0, DEN_) GL_RS1(1, ssq1, DEN_) GL_RS1(2, ssq2, DEN_) GL_RS1(3, ssq3, DEN_) }
;     ...
;   const uint16_t* brow = Bt + (size_t)(n0 + r0 * bm) * K + kc * 8;
;     ...
;     GL_LOAD(2, 0);
; #pragma unroll 1
;     for (int kt = 0; kt < KT; kt += 2) {
;       if (MID && kt == 8) {
;         GL_RS(512.f);
;         __syncthreads();
; #pragma unroll
;         for (int mi = 0; mi < 2; mi++) {
;           f32x16 sv;
; #pragma unroll
;           for (int r = 0; r < 16; r++) sv[r] = rs[64 * wm + 32 * mi + (r & 3) + 8 * (r >> 2) + 4 * lh];
;           acc[mi][0] *= sv; acc[mi][1] *= sv;
;         }
;       }
;       GL_COMPUTE(0);
;       GL_STORE(1, 1, !MID || (kt + 1) < 8);
;       GL_LOAD((kt + 3 < KT ? kt + 3 : KT - 1), 1);
;       __syncthreads();
;       GL_COMPUTE(1);
;       GL_STORE(0, 0, (kt + 2 < KT) && (!MID || (kt + 2) < 8));
;       GL_LOAD((kt + 4 < KT ? kt + 4 : KT - 1), 0);
;       __syncthreads();
;     }
	v_mov_b32_e32 v4, v145
	v_mov_b32_e32 v5, v145
	v_mov_b32_e32 v6, v145
	v_mov_b32_e32 v7, v145
	v_mov_b32_e32 v8, v145
	v_mov_b32_e32 v9, v145
	v_mov_b32_e32 v10, v145
	v_mov_b32_e32 v11, v145
	v_mov_b32_e32 v12, v145
	v_mov_b32_e32 v13, v145
	v_mov_b32_e32 v14, v145
	v_mov_b32_e32 v15, v145
	v_mov_b32_e32 v16, v145
	v_mov_b32_e32 v17, v145
	v_mov_b32_e32 v18, v145
	v_mov_b32_e32 v19, v145
	v_mov_b32_e32 v20, v145
	v_mov_b32_e32 v21, v145
	v_mov_b32_e32 v22, v145
	v_mov_b32_e32 v23, v145
	v_mov_b32_e32 v24, v145
	v_mov_b32_e32 v25, v145
	v_mov_b32_e32 v26, v145
	v_mov_b32_e32 v27, v145
	v_mov_b32_e32 v28, v145
	v_mov_b32_e32 v29, v145
	v_mov_b32_e32 v30, v145
	v_mov_b32_e32 v31, v145
	v_mov_b32_e32 v32, v145
	v_mov_b32_e32 v33, v145
	v_mov_b32_e32 v34, v145
	v_mov_b32_e32 v35, v145
	v_mov_b32_e32 v36, v145
	v_mov_b32_e32 v37, v145
	v_mov_b32_e32 v38, v145
	v_mov_b32_e32 v39, v145
	v_mov_b32_e32 v40, v145
	v_mov_b32_e32 v41, v145
	v_mov_b32_e32 v42, v145
	v_mov_b32_e32 v43, v145
	v_mov_b32_e32 v44, v145
	v_mov_b32_e32 v45, v145
	v_mov_b32_e32 v46, v145
	v_mov_b32_e32 v47, v145
	v_mov_b32_e32 v48, v145
	v_mov_b32_e32 v49, v145
	v_mov_b32_e32 v50, v145
	v_mov_b32_e32 v51, v145
	v_mov_b32_e32 v52, v145
	v_mov_b32_e32 v53, v145
	v_mov_b32_e32 v54, v145
	v_mov_b32_e32 v55, v145
	v_mov_b32_e32 v56, v145
	v_mov_b32_e32 v57, v145
	v_mov_b32_e32 v58, v145
	v_mov_b32_e32 v59, v145
	v_mov_b32_e32 v60, v145
	v_mov_b32_e32 v61, v145
	v_mov_b32_e32 v62, v145
	v_mov_b32_e32 v63, v145
	v_lshl_or_b32 v250, v169, 11, v144
	v_add_u32_e32 v251, 0x10000, v250
	v_add_u32_e32 v252, 0x20000, v250
	v_add_u32_e32 v253, 0x30000, v250
	s_lshl_b32 s98, s46, 11
	s_add_u32 s98, s52, s98
	s_addc_u32 s99, s53, 0
	s_lshl_b32 s100, s36, 18
	s_add_u32 s100, s68, s100
	s_addc_u32 s101, s69, 0
.LBB0_427:
	ds_read_b128 v[128:131], v180
	ds_read_b128 v[132:135], v181 offset:36864
	ds_read_b128 v[136:139], v181 offset:41472
	s_waitcnt lgkmcnt(1)
	v_mfma_f32_32x32x16_bf16 v[48:63], v[128:131], v[132:135], v[48:63]
	s_waitcnt lgkmcnt(0)
	v_mfma_f32_32x32x16_bf16 v[32:47], v[128:131], v[136:139], v[32:47]
	ds_read_b128 v[128:131], v180 offset:4608
	s_waitcnt lgkmcnt(0)
	v_mfma_f32_32x32x16_bf16 v[16:31], v[128:131], v[132:135], v[16:31]
	v_mfma_f32_32x32x16_bf16 v[0:15], v[128:131], v[136:139], v[0:15]
	ds_read_b128 v[128:131], v180 offset:32
	ds_read_b128 v[132:135], v181 offset:36896
	ds_read_b128 v[136:139], v181 offset:41504
	s_waitcnt lgkmcnt(1)
	v_mfma_f32_32x32x16_bf16 v[48:63], v[128:131], v[132:135], v[48:63]
	s_waitcnt lgkmcnt(0)
	v_mfma_f32_32x32x16_bf16 v[32:47], v[128:131], v[136:139], v[32:47]
	ds_read_b128 v[128:131], v180 offset:4640
	s_waitcnt lgkmcnt(0)
	v_mfma_f32_32x32x16_bf16 v[16:31], v[128:131], v[132:135], v[16:31]
	v_mfma_f32_32x32x16_bf16 v[0:15], v[128:131], v[136:139], v[0:15]
	ds_read_b128 v[128:131], v180 offset:4672
	ds_read_b128 v[132:135], v181 offset:41536
	ds_read_b128 v[136:139], v181 offset:36928
	ds_read_b128 v[140:143], v181 offset:36960
	ds_read_b128 v[182:185], v180 offset:64
	ds_read_b128 v[186:189], v180 offset:96
	s_waitcnt lgkmcnt(4)
	v_mfma_f32_32x32x16_bf16 v[0:15], v[128:131], v[132:135], v[0:15]
	s_min_u32 s39, s38, 12
	s_add_i32 s39, s0, s39
	s_and_b32 s48, s39, 15
	s_waitcnt vmcnt(15)
	v_dot2c_f32_bf16_e32 v172, v84, v84
	s_waitcnt vmcnt(13)
	v_dot2c_f32_bf16_e32 v175, v116, v116
	s_waitcnt vmcnt(11)
	v_dot2c_f32_bf16_e32 v176, v120, v120
	s_waitcnt vmcnt(10)
	v_dot2c_f32_bf16_e32 v177, v124, v124
	s_waitcnt lgkmcnt(1)
	v_mfma_f32_32x32x16_bf16 v[48:63], v[182:185], v[136:139], v[48:63]
	v_dot2c_f32_bf16_e32 v172, v85, v85
	v_dot2c_f32_bf16_e32 v175, v117, v117
	v_dot2c_f32_bf16_e32 v176, v121, v121
	v_dot2c_f32_bf16_e32 v177, v125, v125
	v_dot2c_f32_bf16_e32 v172, v86, v86
	v_dot2c_f32_bf16_e32 v175, v118, v118
	v_dot2c_f32_bf16_e32 v176, v122, v122
	v_mfma_f32_32x32x16_bf16 v[32:47], v[182:185], v[132:135], v[32:47]
	v_dot2c_f32_bf16_e32 v177, v126, v126
	v_mfma_f32_32x32x16_bf16 v[16:31], v[128:131], v[136:139], v[16:31]
	ds_read_b128 v[128:131], v181 offset:41568
	ds_read_b128 v[132:135], v180 offset:4704
	ds_write_b128 v170, v[84:87] offset:18432
	s_waitcnt vmcnt(9)
	ds_write_b128 v170, v[64:67] offset:55296
	ds_write_b128 v171, v[116:119] offset:18432
	s_waitcnt vmcnt(8)
	ds_write_b128 v171, v[68:71] offset:55296
	ds_write_b128 v173, v[120:123] offset:18432
	s_waitcnt vmcnt(9)
	ds_write_b128 v173, v[72:75] offset:55296
	ds_write_b128 v174, v[124:127] offset:18432
	s_waitcnt vmcnt(8)
	ds_write_b128 v174, v[76:79] offset:55296
	s_lshl_b32 s48, s48, 7
	s_add_u32 s50, s98, s48
	s_addc_u32 s51, s99, 0
	s_add_u32 s48, s100, s48
	s_addc_u32 s49, s101, 0
	s_waitcnt lgkmcnt(10)
	v_mfma_f32_32x32x16_bf16 v[48:63], v[186:189], v[140:143], v[48:63]
	global_load_dwordx4 v[136:139], v252, s[50:51]
	s_waitcnt lgkmcnt(9)
	v_mfma_f32_32x32x16_bf16 v[32:47], v[186:189], v[128:131], v[32:47]
	s_waitcnt lgkmcnt(8)
	v_mfma_f32_32x32x16_bf16 v[16:31], v[132:135], v[140:143], v[16:31]
	global_load_dwordx4 v[140:143], v253, s[50:51]
	global_load_dwordx4 v[72:75], v252, s[48:49]
	s_nop 0
	global_load_dwordx4 v[76:79], v253, s[48:49]
	v_mfma_f32_32x32x16_bf16 v[0:15], v[132:135], v[128:131], v[0:15]
	global_load_dwordx4 v[128:131], v250, s[50:51]
	global_load_dwordx4 v[132:135], v251, s[50:51]
	global_load_dwordx4 v[64:67], v250, s[48:49]
	s_nop 0
	global_load_dwordx4 v[68:71], v251, s[48:49]
	s_waitcnt lgkmcnt(0)
	s_barrier
; #define GL_LOAD(KT_, S) { int kt_ = MID ? (((KT_) & 8) | (((KT_) + rot) & 7)) : (((KT_) + rot) & (KT - 1)); kt_ &= ktmask; asm volatile("" : "+s"(kt_)); GL_LD1(0, S) GL_LD1(1, S) GL_LD1(2, S) GL_LD1(3, S) }
; #define GL_STORE(BUF_, S, DOSSQ_) { const bool dossq_ = (DOSSQ_); GL_ST1(0, S, BUF_, ssq0) GL_ST1(1, S, BUF_, ssq1) GL_ST1(2, S, BUF_, ssq2) GL_ST1(3, S, BUF_, ssq3) }
; #define GL_RS(DEN_) { GL_RS1(0, ssq0, DEN_) GL_RS1(1, ssq1, DEN_) GL_RS1(2, ssq2, DEN_) GL_RS1(3, ssq3, DEN_) }
;     ...
;     GL_LOAD(2, 0);
; #pragma unroll 1
;     for (int kt = 0; kt < KT; kt += 2) {
;       if (MID && kt == 8) {
;         GL_RS(512.f);
;         __syncthreads();
; #pragma unroll
;         for (int mi = 0; mi < 2; mi++) {
;           f32x16 sv;
; #pragma unroll
;           for (int r = 0; r < 16; r++) sv[r] = rs[64 * wm + 32 * mi + (r & 3) + 8 * (r >> 2) + 4 * lh];
;           acc[mi][0] *= sv; acc[mi][1] *= sv;
;         }
;       }
;       GL_COMPUTE(0);
;       GL_STORE(1, 1, !MID || (kt + 1) < 8);
;       GL_LOAD((kt + 3 < KT ? kt + 3 : KT - 1), 1);
;       __syncthreads();
;       GL_COMPUTE(1);
;       GL_STORE(0, 0, (kt + 2 < KT) && (!MID || (kt + 2) < 8));
;       GL_LOAD((kt + 4 < KT ? kt + 4 : KT - 1), 0);
;       __syncthreads();
;     }
;   }
;   if (!MID) GL_RS((float)K);
	ds_read_b128 v[182:185], v180 offset:23040
	ds_read_b128 v[186:189], v181 offset:59904
	ds_read_b128 v[190:193], v181 offset:55296
	ds_read_b128 v[194:197], v181 offset:55328
	ds_read_b128 v[198:201], v180 offset:18432
	ds_read_b128 v[202:205], v180 offset:18464
	s_waitcnt lgkmcnt(1)
	v_mfma_f32_32x32x16_bf16 v[48:63], v[198:201], v[190:193], v[48:63]
	v_mfma_f32_32x32x16_bf16 v[32:47], v[198:201], v[186:189], v[32:47]
	v_mfma_f32_32x32x16_bf16 v[16:31], v[182:185], v[190:193], v[16:31]
	v_mfma_f32_32x32x16_bf16 v[0:15], v[182:185], v[186:189], v[0:15]
	ds_read_b128 v[182:185], v181 offset:59936
	ds_read_b128 v[186:189], v180 offset:23072
	s_waitcnt lgkmcnt(2)
	v_mfma_f32_32x32x16_bf16 v[48:63], v[202:205], v[194:197], v[48:63]
	s_waitcnt lgkmcnt(1)
	v_mfma_f32_32x32x16_bf16 v[32:47], v[202:205], v[182:185], v[32:47]
	s_waitcnt lgkmcnt(0)
	v_mfma_f32_32x32x16_bf16 v[16:31], v[186:189], v[194:197], v[16:31]
	v_mfma_f32_32x32x16_bf16 v[0:15], v[186:189], v[182:185], v[0:15]
	ds_read_b128 v[182:185], v180 offset:23104
	ds_read_b128 v[186:189], v181 offset:59968
	ds_read_b128 v[190:193], v181 offset:55360
	ds_read_b128 v[194:197], v181 offset:55392
	ds_read_b128 v[198:201], v180 offset:18496
	ds_read_b128 v[202:205], v180 offset:18528
	s_waitcnt lgkmcnt(4)
	v_mfma_f32_32x32x16_bf16 v[0:15], v[182:185], v[186:189], v[0:15]
	s_min_u32 s48, s38, 11
	s_add_i32 s48, s1, s48
	s_and_b32 s48, s48, 15
	s_add_i32 s39, s38, 2
	s_waitcnt vmcnt(2)
	v_mov_b32_e32 v118, v134
	v_mov_b32_e32 v117, v133
	v_mov_b32_e32 v116, v132
	s_waitcnt lgkmcnt(1)
	v_mfma_f32_32x32x16_bf16 v[32:47], v[198:201], v[186:189], v[32:47]
	v_mov_b32_e32 v122, v138
	v_mov_b32_e32 v121, v137
	v_mov_b32_e32 v120, v136
	v_mov_b32_e32 v126, v142
	v_mov_b32_e32 v125, v141
	v_mov_b32_e32 v124, v140
	v_mfma_f32_32x32x16_bf16 v[16:31], v[182:185], v[190:193], v[16:31]
	ds_read_b128 v[182:185], v181 offset:60000
	ds_read_b128 v[186:189], v180 offset:23136
	ds_write_b128 v170, v[80:83]
	ds_write_b128 v170, v[108:111] offset:36864
	ds_write_b128 v171, v[96:99]
	ds_write_b128 v171, v[104:107] offset:36864
	ds_write_b128 v173, v[92:95]
	ds_write_b128 v173, v[100:103] offset:36864
	ds_write_b128 v174, v[88:91]
	ds_write_b128 v174, v[112:115] offset:36864
	s_lshl_b32 s48, s48, 7
	s_add_u32 s50, s98, s48
	s_addc_u32 s51, s99, 0
	s_add_u32 s48, s100, s48
	s_addc_u32 s49, s101, 0
	s_waitcnt lgkmcnt(9)
	v_mfma_f32_32x32x16_bf16 v[32:47], v[202:205], v[182:185], v[32:47]
	s_cmp_lt_u32 s38, 14
	s_waitcnt lgkmcnt(8)
	v_mfma_f32_32x32x16_bf16 v[0:15], v[186:189], v[182:185], v[0:15]
	v_mov_b32_e32 v184, v175
	v_dot2c_f32_bf16_e32 v184, v119, v119
	v_mov_b32_e32 v185, v172
	v_mov_b32_e32 v182, v177
	v_dot2c_f32_bf16_e32 v185, v87, v87
	v_mov_b32_e32 v175, v184
	v_mov_b32_e32 v183, v176
	v_dot2c_f32_bf16_e32 v182, v127, v127
	v_dot2c_f32_bf16_e32 v175, v96, v96
	v_dot2c_f32_bf16_e32 v183, v123, v123
	v_mov_b32_e32 v172, v185
	v_dot2c_f32_bf16_e32 v175, v97, v97
	v_mov_b32_e32 v177, v182
	v_dot2c_f32_bf16_e32 v172, v80, v80
	v_dot2c_f32_bf16_e32 v175, v98, v98
	v_mov_b32_e32 v176, v183
	v_dot2c_f32_bf16_e32 v177, v88, v88
	global_load_dwordx4 v[108:111], v250, s[48:49]
	v_dot2c_f32_bf16_e32 v172, v81, v81
	v_dot2c_f32_bf16_e32 v175, v99, v99
	v_dot2c_f32_bf16_e32 v176, v92, v92
	v_dot2c_f32_bf16_e32 v177, v89, v89
	global_load_dwordx4 v[96:99], v251, s[50:51]
	v_dot2c_f32_bf16_e32 v172, v82, v82
	v_dot2c_f32_bf16_e32 v176, v93, v93
	v_dot2c_f32_bf16_e32 v177, v90, v90
	global_load_dwordx4 v[104:107], v251, s[48:49]
	v_dot2c_f32_bf16_e32 v172, v83, v83
	v_dot2c_f32_bf16_e32 v176, v94, v94
	v_dot2c_f32_bf16_e32 v177, v91, v91
	global_load_dwordx4 v[80:83], v250, s[50:51]
	v_dot2c_f32_bf16_e32 v176, v95, v95
	global_load_dwordx4 v[88:91], v253, s[50:51]
	global_load_dwordx4 v[92:95], v252, s[50:51]
	global_load_dwordx4 v[112:115], v253, s[48:49]
	global_load_dwordx4 v[100:103], v252, s[48:49]
	v_mfma_f32_32x32x16_bf16 v[48:63], v[198:201], v[190:193], v[48:63]
	v_mov_b32_e32 v87, v131
	v_mov_b32_e32 v86, v130
	v_mov_b32_e32 v85, v129
	v_mov_b32_e32 v84, v128
	v_mov_b32_e32 v119, v135
	v_mov_b32_e32 v123, v139
	v_mov_b32_e32 v127, v143
	v_mfma_f32_32x32x16_bf16 v[48:63], v[202:205], v[194:197], v[48:63]
	s_mov_b32 s38, s39
	s_waitcnt lgkmcnt(0)
	s_barrier
	v_mfma_f32_32x32x16_bf16 v[16:31], v[186:189], v[194:197], v[16:31]
	s_cbranch_scc1 .LBB0_427
	s_waitcnt vmcnt(9)
	v_and_b32_e32 v65, 64, v162
	v_xor_b32_e32 v64, 1, v162
	v_add_u32_e32 v65, 64, v65
	v_cmp_lt_i32_e32 vcc, v64, v65
	v_xor_b32_e32 v67, 2, v162
	s_nop 0
	v_cndmask_b32_e32 v64, v162, v64, vcc
	v_lshlrev_b32_e32 v64, 2, v64
	ds_bpermute_b32 v66, v64, v185
	v_cmp_lt_i32_e32 vcc, v67, v65
	s_waitcnt lgkmcnt(0)
	v_add_f32_e32 v66, v185, v66
	v_cndmask_b32_e32 v67, v162, v67, vcc
	v_lshlrev_b32_e32 v67, 2, v67
	s_waitcnt vmcnt(8)
	ds_bpermute_b32 v68, v67, v66
	s_waitcnt lgkmcnt(0)
	v_add_f32_e32 v69, v66, v68
	v_xor_b32_e32 v66, 4, v162
	v_cmp_lt_i32_e32 vcc, v66, v65
	s_nop 1
	v_cndmask_b32_e32 v66, v162, v66, vcc
	v_lshlrev_b32_e32 v68, 2, v66
	ds_bpermute_b32 v70, v68, v69
	v_cmp_eq_u32_e32 vcc, 0, v168
	v_lshl_add_u32 v66, v169, 2, 16
	s_and_saveexec_b64 s[38:39], vcc
	s_cbranch_execz .LBB0_430
	s_waitcnt lgkmcnt(0)
	v_add_f32_e32 v69, v69, v70
	v_fmamk_f32 v69, v69, 0x3a800000, v164
	v_mul_f32_e32 v70, 0x4b800000, v69
	v_cmp_gt_f32_e64 s[0:1], s41, v69
	s_nop 1
	v_cndmask_b32_e64 v69, v69, v70, s[0:1]
	v_rsq_f32_e32 v69, v69
	s_nop 0
	v_mul_f32_e32 v70, 0x45800000, v69
	v_cndmask_b32_e64 v69, v69, v70, s[0:1]
	v_add_u32_e32 v70, 0x12000, v66
	ds_write_b32 v70, v69
